# v27b + RWKV next-chunk LDS staging and its global loads moved from the solve interval to the first barrier interval (alone)
# baseline (speedup 1.0000x reference)
; __device__ __forceinline__ void rwkv_chunk_item(const P& p, const Ctx& c, int seg, int w, bool save) {
;     ...
;     auto gload = [&](int ch, int tidv) { const int t = tidv >> 5, j0 = (tidv & 31) * 2; const size_t go = ((size_t)b * SEGT + ch * 16 + t) * DMIX + hh * 64 + j0;
;         ga = *(const unsigned*)(SA + go); gb = *(const unsigned*)(SB + go); gk = *(const unsigned*)(SK + go); gr = *(const unsigned*)(SR + go); gv = *(const unsigned*)(SV + go);
;         if (tidv < 64) gg = GTB[((size_t)(b * 32 + ch) * 24 + hh) * 64 + tidv]; };
;     auto lstore = [&](int pb, int tidv) { const int t = tidv >> 5, j0 = (tidv & 31) * 2;
;         LAS bf16_t* EA = (LAS bf16_t*)(OB + pb * OPB + O_EA); LAS bf16_t* EB = (LAS bf16_t*)(OB + pb * OPB + O_EB); LAS bf16_t* EBT = (LAS bf16_t*)(OB + pb * OPB + O_EBT);
;         LAS bf16_t* UV = (LAS bf16_t*)(OB + pb * OPB + O_UV); LAS float* GT = (LAS float*)(OB + pb * OPB + O_GT);
;         *(LAS unsigned*)(EA + t * 72 + j0) = ga; *(LAS unsigned*)(EA + (16 + t) * 72 + j0) = gr;
;         *(LAS unsigned*)(EB + t * 72 + j0) = gb; *(LAS unsigned*)(EB + (16 + t) * 72 + j0) = gk;
;         EBT[j0 * 40 + t] = (bf16_t)(gb & 0xFFFFu); EBT[(j0 + 1) * 40 + t] = (bf16_t)(gb >> 16); EBT[j0 * 40 + 16 + t] = (bf16_t)(gk & 0xFFFFu); EBT[(j0 + 1) * 40 + 16 + t] = (bf16_t)(gk >> 16);
;         UV[j0 * 40 + 16 + t] = (bf16_t)(gv & 0xFFFFu); UV[(j0 + 1) * 40 + 16 + t] = (bf16_t)(gv >> 16); UV[j0 * 40 + t] = 0; UV[(j0 + 1) * 40 + t] = 0;
;         if (tidv < 64) GT[tidv] = gg; };
;     ...
;         lds_barrier();
;         f32x4 Zt = (f32x4){0.f, 0.f, 0.f, 0.f};
;         if (c.wv < 4 && ch > 0) efinish(ch - 1);
;         if (c.wv >= 4) {
;             f32x4 Xt = (f32x4){0.f, 0.f, 0.f, 0.f};
; #pragma unroll
;             for (int kk = 0; kk < 2; ++kk) { const bf16x8 a = *(const LAS bf16x8*)(S0I + (mtq * 16 + l15) * 72 + kk * 32 + quad * 8);
;                 Xt = mfma16(a, *(const LAS bf16x8*)(EA + l15 * 72 + kk * 32 + quad * 8), Xt); Zt = mfma16(a, *(const LAS bf16x8*)(EA + (16 + l15) * 72 + kk * 32 + quad * 8), Zt); }
;             Xt = mfma16(*(const LAS bf16x8*)(UV + (mtq * 16 + l15) * 40 + quad * 8), *(const LAS bf16x8*)(MT1 + l15 * 40 + quad * 8), Xt);
; #pragma unroll
;             for (int jj = 0; jj < 4; ++jj) XF[(mtq * 16 + quad * 4 + jj) * 17 + l15] = Xt[jj];
;         }
;         lds_barrier();
;         if (ch + 1 < SEGT / 16) lstore(pb ^ 1, tidv);
.LBB0_886:
	v_mov_b32_e32 v44, v55
	v_mov_b32_e32 v83, v63
	v_mov_b32_e32 v82, v59
	s_waitcnt lgkmcnt(0)
	s_barrier
	s_cmp_eq_u32 s86, 31
	s_cbranch_scc1 .Lrw_nostage
	v_ashrrev_i32_e32 v46, 5, v44
	v_lshlrev_b32_e32 v45, 1, v44
	v_cmp_gt_i32_e64 s[2:3], 64, v44
	s_and_b32 s78, s86, 1
	s_xor_b32 s78, s78, 1
	v_and_b32_e32 v47, 62, v45
	s_mulk_i32 s78, 0x5c00
	s_add_i32 s89, s78, 0
	v_mul_lo_u32 v48, v46, s63
	v_lshlrev_b32_e32 v49, 1, v47
	v_mad_u32_u24 v47, v47, 40, v46
	v_add3_u32 v48, s89, v48, v49
	v_lshl_add_u32 v47, v47, 1, s89
	s_waitcnt vmcnt(1)
	ds_write2st64_b32 v48, v71, v76 offset1:9
	ds_write2st64_b32 v48, v74, v75 offset0:18 offset1:27
	ds_write_b16 v47, v74 offset:9216
	ds_write_b16_d16_hi v47, v74 offset:9296
	ds_write_b16 v47, v75 offset:9248
	ds_write_b16_d16_hi v47, v75 offset:9328
	s_waitcnt vmcnt(0)
	ds_write_b16 v47, v79 offset:14368
	ds_write_b16_d16_hi v47, v79 offset:14448
	ds_write_b16 v47, v5 offset:14336
	ds_write_b16 v47, v5 offset:14416
	s_and_saveexec_b64 s[78:79], s[2:3]
	v_lshl_add_u32 v47, v44, 2, s89
	ds_write_b32 v47, v27 offset:23296
	s_or_b64 exec, exec, s[78:79]
	s_cmp_gt_u32 s86, 29
	s_cbranch_scc1 .Lrw_nostage
	v_ashrrev_i32_e32 v47, 31, v46
	v_lshl_add_u64 v[46:47], s[76:77], 0, v[46:47]
	v_mov_b64_e32 v[48:49], s[14:15]
	v_mad_u64_u32 v[48:49], s[2:3], v46, s58, v[48:49]
	v_mov_b32_e32 v46, v49
	v_mad_u64_u32 v[46:47], s[2:3], v47, s58, v[46:47]
	v_and_or_b32 v48, v45, 62, v48
	v_mov_b32_e32 v49, v46
	v_lshlrev_b64 v[46:47], 1, v[48:49]
	v_lshl_add_u64 v[48:49], s[16:17], 0, v[46:47]
	global_load_dword v71, v[48:49], off
	v_lshl_add_u64 v[48:49], s[26:27], 0, v[46:47]
	global_load_dword v74, v[48:49], off
	v_lshl_add_u64 v[48:49], s[20:21], 0, v[46:47]
	global_load_dword v75, v[48:49], off
	v_lshl_add_u64 v[48:49], s[30:31], 0, v[46:47]
	v_lshl_add_u64 v[46:47], s[24:25], 0, v[46:47]
	global_load_dword v76, v[48:49], off
	global_load_dword v79, v[46:47], off
	v_cmp_gt_i32_e32 vcc, 64, v44
	s_and_saveexec_b64 s[2:3], vcc
	s_cbranch_execz .Lrw_gg_done
	s_add_i32 s78, s85, s86
	s_mul_hi_i32 s79, s78, 24
	s_mul_i32 s78, s78, 24
	s_add_u32 s78, s78, s46
	s_addc_u32 s79, s79, s47
	s_lshl_b64 s[78:79], s[78:79], 8
	s_add_u32 s78, s81, s78
	v_ashrrev_i32_e32 v45, 31, v44
	s_addc_u32 s79, s82, s79
	v_lshl_add_u64 v[44:45], v[44:45], 2, s[78:79]
	global_load_dword v27, v[44:45], off
